# NSA unit epilogue: gate loads and the 8 o_cmp loads issued up front (one round trip instead of ten serialised load/wait/store steps), on top of the ph0 changes
# speedup vs baseline: 1.0337x; 1.0036x over previous
; __device__ __forceinline__ unsigned pk2(float lo, float hi) { return f2bf(lo) | (f2bf(hi) << 16); }
; __device__ __forceinline__ float bf2f(bf16 h) { return __uint_as_float(((unsigned)h) << 16); }
; __device__ __forceinline__ float sigmoidf_(float x) { return 1.0f / (1.0f + __expf(-x)); }
; __device__ __forceinline__ unsigned range_mask(int lo, int hi_incl) { const unsigned up = (hi_incl >= 31) ? 0xffffffffu : ((1u << (hi_incl + 1)) - 1u); return up & ~((1u << lo) - 1u); }
; __device__ __forceinline__ void phase_nsa_mfma(const PT a, unsigned char* ldsb, int tid, int lane, int wave, int bid, int nblk) {
;     ...
;         const float isel = 1.0f / (l + __shfl_xor(l, 32));
;         m = -1e30f; l = 0.f;
;         const int wlo = (t0 - 511 > 0 ? t0 - 511 : 0) >> 6, whi = (t0 + 31) >> 6;
;         attn_pass<64, 2, 8960, true>(range_mask(wlo, whi), base_b, 0, 1, OFF_BKV + (8 + g) * 64, OFF_BKV + (10 + g) * 64, Ks, Vt, 0, qf, m, l, Ow, tab, bk, tq, 511, 0xffffffffu, t0 + 31, -(1 << 20), tid, l32, hi);
;         const float iwin = 1.0f / (l + __shfl_xor(l, 32));
;         const bf16* gp = proj + (size_t)tok * NP + OFF_BG + hh * 3;
;         const float g0 = sigmoidf_(bf2f(gp[0])), g1 = sigmoidf_(bf2f(gp[1])) * isel, g2 = sigmoidf_(bf2f(gp[2])) * iwin;
; #pragma unroll
;         for (int ds = 0; ds < 2; ++ds)
; #pragma unroll
;             for (int i4 = 0; i4 < 4; ++i4) { const int d = ds * 32 + i4 * 8 + 4 * hi; const size_t off = (size_t)tok * 1024 + hh * 64 + d;
;                 const f32x4 oc = *(const f32x4*)(ocmp + off);
;                 const float r0 = g0 * oc.x + g1 * Os[ds][i4 * 4 + 0] + g2 * Ow[ds][i4 * 4 + 0], r1 = g0 * oc.y + g1 * Os[ds][i4 * 4 + 1] + g2 * Ow[ds][i4 * 4 + 1];
;                 const float r2 = g0 * oc.z + g1 * Os[ds][i4 * 4 + 2] + g2 * Ow[ds][i4 * 4 + 2], r3 = g0 * oc.w + g1 * Os[ds][i4 * 4 + 3] + g2 * Ow[ds][i4 * 4 + 3];
;                 u32x2 w; w.x = pk2(r0, r1); w.y = pk2(r2, r3); *(u32x2*)(ob + (size_t)tok * KCAT + 512 + hh * 64 + d) = w; }
.LBB0_110:
	s_waitcnt lgkmcnt(0)
	s_mul_i32 s4, s18, 3
	s_ashr_i32 s5, s4, 31
	v_lshl_add_u64 v[142:143], s[4:5], 1, v[152:153]
	s_mov_b64 s[4:5], 0x3200
	v_lshl_add_u64 v[142:143], v[142:143], 0, s[4:5]
	v_readlane_b32 s4, v253, 54
	v_readlane_b32 s5, v253, 55
	global_load_dword v140, v[142:143], off
	global_load_ushort v141, v[142:143], off offset:4
	v_lshlrev_b64 v[136:137], 12, v[150:151]
	v_mov_b32_e32 v138, v154
	v_ashrrev_i32_e32 v139, 31, v154
	v_lshl_add_u64 v[136:137], s[4:5], 0, v[136:137]
	v_lshl_add_u64 v[136:137], s[0:1], 2, v[136:137]
	v_lshl_add_u64 v[136:137], v[138:139], 2, v[136:137]
	global_load_dwordx4 v[84:87], v[136:137], off
	global_load_dwordx4 v[92:95], v[136:137], off offset:32
	global_load_dwordx4 v[96:99], v[136:137], off offset:64
	global_load_dwordx4 v[100:103], v[136:137], off offset:96
	global_load_dwordx4 v[106:109], v[136:137], off offset:128
	global_load_dwordx4 v[124:127], v[136:137], off offset:160
	global_load_dwordx4 v[128:131], v[136:137], off offset:192
	global_load_dwordx4 v[132:135], v[136:137], off offset:224
	v_add_f32_e32 v0, v180, v181
	s_waitcnt vmcnt(11)
	v_div_scale_f32 v2, s[4:5], v0, v0, 1.0
	v_rcp_f32_e32 v3, v2
	s_mul_i32 s4, s18, 3
	s_ashr_i32 s5, s4, 31
	s_movk_i32 s2, 0x3000
	v_fma_f32 v4, -v2, v3, 1.0
	v_fmac_f32_e32 v3, v4, v3
	v_div_scale_f32 v4, vcc, 1.0, v0, 1.0
	v_mul_f32_e32 v5, v4, v3
	s_waitcnt vmcnt(10)
	v_fma_f32 v6, -v2, v5, v4
	v_fmac_f32_e32 v5, v6, v3
	v_fma_f32 v2, -v2, v5, v4
	v_div_fmas_f32 v2, v2, v3, v5
	v_div_fixup_f32 v6, v2, v0, 1.0
	v_lshl_add_u64 v[2:3], s[4:5], 1, v[152:153]
	s_mov_b64 s[4:5], 0x3200
	v_lshl_add_u64 v[4:5], v[2:3], 0, s[4:5]
	v_add_co_u32_e32 v2, vcc, s2, v2
	ds_bpermute_b32 v188, v113, v156
	s_nop 0
	v_addc_co_u32_e32 v3, vcc, 0, v3, vcc
	s_waitcnt vmcnt(9)
	v_mov_b32_e32 v2, v140
	v_ashrrev_i32_e32 v155, 31, v154
	s_movk_i32 s2, 0x1400
	v_mov_b32_e32 v80, v32
	v_mov_b32_e32 v81, v34
	v_mov_b32_e32 v34, v33
	v_mov_b32_e32 v32, v36
	v_mov_b32_e32 v33, v38
	v_mov_b32_e32 v38, v37
	s_add_i32 s37, s37, s58
	s_cmpk_lt_i32 s37, 0x200
	v_lshlrev_b32_e32 v0, 16, v2
	v_mul_f32_e32 v0, 0xbfb8aa3b, v0
	v_exp_f32_e32 v0, v0
	v_and_b32_e32 v2, 0xffff0000, v2
	v_mul_f32_e32 v2, 0xbfb8aa3b, v2
	v_exp_f32_e32 v2, v2
	v_add_f32_e32 v0, 1.0, v0
	v_div_scale_f32 v3, s[4:5], v0, v0, 1.0
	v_rcp_f32_e32 v7, v3
	v_add_f32_e32 v2, 1.0, v2
	v_fma_f32 v8, -v3, v7, 1.0
	v_fmac_f32_e32 v7, v8, v7
	v_div_scale_f32 v8, vcc, 1.0, v0, 1.0
	v_mul_f32_e32 v9, v8, v7
	v_fma_f32 v10, -v3, v9, v8
	v_fmac_f32_e32 v9, v10, v7
	v_fma_f32 v3, -v3, v9, v8
	v_div_fmas_f32 v3, v3, v7, v9
	v_div_fixup_f32 v0, v3, v0, 1.0
	v_div_scale_f32 v3, s[4:5], v2, v2, 1.0
	v_rcp_f32_e32 v7, v3
	s_nop 0
	v_fma_f32 v8, -v3, v7, 1.0
	v_fmac_f32_e32 v7, v8, v7
	v_div_scale_f32 v8, vcc, 1.0, v2, 1.0
	v_mul_f32_e32 v9, v8, v7
	v_fma_f32 v10, -v3, v9, v8
	v_fmac_f32_e32 v9, v10, v7
	v_fma_f32 v3, -v3, v9, v8
	v_div_fmas_f32 v3, v3, v7, v9
	v_div_fixup_f32 v2, v3, v2, 1.0
	v_mul_f32_e32 v6, v6, v2
	s_waitcnt vmcnt(8)
	v_mov_b32_e32 v2, v141
	v_lshlrev_b32_e32 v2, 16, v2
	v_mul_f32_e32 v2, 0xbfb8aa3b, v2
	v_exp_f32_e32 v157, v2
	s_waitcnt lgkmcnt(0)
	v_pk_add_f32 v[2:3], v[156:157], v[188:189]
	s_nop 0
	v_div_scale_f32 v4, s[4:5], v3, v3, 1.0
	v_rcp_f32_e32 v5, v4
	s_nop 0
	v_fma_f32 v7, -v4, v5, 1.0
	v_fmac_f32_e32 v5, v7, v5
	v_div_scale_f32 v7, vcc, 1.0, v3, 1.0
	v_mul_f32_e32 v8, v7, v5
	v_fma_f32 v9, -v4, v8, v7
	v_fmac_f32_e32 v8, v9, v5
	v_fma_f32 v4, -v4, v8, v7
	v_div_fmas_f32 v4, v4, v5, v8
	v_div_fixup_f32 v7, v4, v3, 1.0
	v_div_scale_f32 v3, s[4:5], v2, v2, 1.0
	v_rcp_f32_e32 v4, v3
	v_readlane_b32 s4, v253, 54
	v_readlane_b32 s5, v253, 55
	v_pk_mul_f32 v[80:81], v[80:81], v[6:7] op_sel_hi:[1,0]
	v_fma_f32 v5, -v3, v4, 1.0
	v_fmac_f32_e32 v4, v5, v4
	v_div_scale_f32 v5, vcc, 1.0, v2, 1.0
	v_mul_f32_e32 v8, v5, v4
	v_fma_f32 v9, -v3, v8, v5
	v_fmac_f32_e32 v8, v9, v4
	v_fma_f32 v3, -v3, v8, v5
	v_div_fmas_f32 v3, v3, v4, v8
	v_div_fixup_f32 v12, v3, v2, 1.0
	v_lshlrev_b64 v[2:3], 12, v[150:151]
	v_lshl_add_u64 v[2:3], s[4:5], 0, v[2:3]
	v_lshl_add_u64 v[2:3], s[0:1], 2, v[2:3]
	v_mov_b64_e32 v[4:5], s[34:35]
	v_mad_u64_u32 v[4:5], s[4:5], v150, s2, v[4:5]
	v_lshl_add_u64 v[8:9], v[154:155], 2, v[2:3]
	v_lshl_add_u64 v[10:11], s[0:1], 1, v[4:5]
	s_waitcnt vmcnt(0)
; __device__ __forceinline__ unsigned pk2(float lo, float hi) { return f2bf(lo) | (f2bf(hi) << 16); }
; __device__ __forceinline__ void phase_nsa_mfma(const PT a, unsigned char* ldsb, int tid, int lane, int wave, int bid, int nblk) {
;     ...
;             for (int i4 = 0; i4 < 4; ++i4) { const int d = ds * 32 + i4 * 8 + 4 * hi; const size_t off = (size_t)tok * 1024 + hh * 64 + d;
;                 const f32x4 oc = *(const f32x4*)(ocmp + off);
;                 const float r0 = g0 * oc.x + g1 * Os[ds][i4 * 4 + 0] + g2 * Ow[ds][i4 * 4 + 0], r1 = g0 * oc.y + g1 * Os[ds][i4 * 4 + 1] + g2 * Ow[ds][i4 * 4 + 1];
;                 const float r2 = g0 * oc.z + g1 * Os[ds][i4 * 4 + 2] + g2 * Ow[ds][i4 * 4 + 2], r3 = g0 * oc.w + g1 * Os[ds][i4 * 4 + 3] + g2 * Ow[ds][i4 * 4 + 3];
;                 u32x2 w; w.x = pk2(r0, r1); w.y = pk2(r2, r3); *(u32x2*)(ob + (size_t)tok * KCAT + 512 + hh * 64 + d) = w; }
	s_nop 1
	v_mov_b64_e32 v[2:3], v[84:85]
	v_mov_b64_e32 v[4:5], v[86:87]
	v_lshl_add_u64 v[10:11], v[154:155], 1, v[10:11]
	s_mov_b64 s[0:1], 0x23800400
	v_mov_b32_e32 v14, v2
	v_mov_b32_e32 v15, v4
	v_pk_fma_f32 v[14:15], v[14:15], v[0:1], v[80:81] op_sel_hi:[1,0,1]
	v_mov_b32_e32 v80, v64
	v_mov_b32_e32 v81, v66
	v_mul_f32_e32 v2, v12, v7
	v_pk_fma_f32 v[12:13], v[80:81], v[2:3], v[14:15] op_sel_hi:[1,0,1]
	v_mov_b32_e32 v4, v3
	v_pk_mul_f32 v[14:15], v[34:35], v[6:7] op_sel_hi:[1,0]
	v_mov_b32_e32 v66, v65
	v_pk_fma_f32 v[4:5], v[4:5], v[0:1], v[14:15] op_sel_hi:[1,0,1]
	v_and_b32_sdwa v7, v12, v225 dst_sel:DWORD dst_unused:UNUSED_PAD src0_sel:WORD_1 src1_sel:DWORD
	v_pk_fma_f32 v[4:5], v[66:67], v[2:3], v[4:5] op_sel_hi:[1,0,1]
	v_and_b32_sdwa v3, v13, v225 dst_sel:DWORD dst_unused:UNUSED_PAD src0_sel:WORD_1 src1_sel:DWORD
	v_add3_u32 v7, v12, v7, s72
	v_add3_u32 v3, v13, v3, s72
	v_and_b32_sdwa v12, v5, v225 dst_sel:DWORD dst_unused:UNUSED_PAD src0_sel:WORD_1 src1_sel:DWORD
	v_and_b32_sdwa v13, v4, v225 dst_sel:DWORD dst_unused:UNUSED_PAD src0_sel:WORD_1 src1_sel:DWORD
	v_add3_u32 v5, v5, v12, s72
	v_add3_u32 v4, v4, v13, s72
	v_and_b32_e32 v5, 0xffff0000, v5
	v_and_b32_e32 v4, 0xffff0000, v4
	v_or_b32_sdwa v13, v5, v3 dst_sel:DWORD dst_unused:UNUSED_PAD src0_sel:DWORD src1_sel:WORD_1
	v_or_b32_sdwa v12, v4, v7 dst_sel:DWORD dst_unused:UNUSED_PAD src0_sel:DWORD src1_sel:WORD_1
	v_lshl_add_u64 v[4:5], v[10:11], 0, s[0:1]
	s_mov_b32 s0, 0x23800000
	v_add_co_u32_e32 v10, vcc, s0, v10
	v_pk_mul_f32 v[32:33], v[32:33], v[6:7] op_sel_hi:[1,0]
	s_nop 0
	v_addc_co_u32_e32 v11, vcc, 0, v11, vcc
	global_store_dwordx2 v[10:11], v[12:13], off offset:1024
	s_nop 1
	v_mov_b64_e32 v[10:11], v[92:93]
	v_mov_b64_e32 v[12:13], v[94:95]
	v_mov_b32_e32 v14, v10
	v_mov_b32_e32 v15, v12
	v_mov_b32_e32 v12, v11
	v_pk_mul_f32 v[10:11], v[38:39], v[6:7] op_sel_hi:[1,0]
	v_pk_fma_f32 v[14:15], v[14:15], v[0:1], v[32:33] op_sel_hi:[1,0,1]
	v_mov_b32_e32 v33, v70
	v_pk_fma_f32 v[10:11], v[12:13], v[0:1], v[10:11] op_sel_hi:[1,0,1]
	v_mov_b32_e32 v70, v69
	v_mov_b32_e32 v32, v68
	v_pk_fma_f32 v[10:11], v[70:71], v[2:3], v[10:11] op_sel_hi:[1,0,1]
	v_pk_fma_f32 v[14:15], v[32:33], v[2:3], v[14:15] op_sel_hi:[1,0,1]
	v_and_b32_sdwa v12, v11, v225 dst_sel:DWORD dst_unused:UNUSED_PAD src0_sel:WORD_1 src1_sel:DWORD
	v_and_b32_sdwa v13, v10, v225 dst_sel:DWORD dst_unused:UNUSED_PAD src0_sel:WORD_1 src1_sel:DWORD
	v_and_b32_sdwa v3, v15, v225 dst_sel:DWORD dst_unused:UNUSED_PAD src0_sel:WORD_1 src1_sel:DWORD
	v_and_b32_sdwa v7, v14, v225 dst_sel:DWORD dst_unused:UNUSED_PAD src0_sel:WORD_1 src1_sel:DWORD
	v_add3_u32 v11, v11, v12, s72
	v_add3_u32 v10, v10, v13, s72
	v_add3_u32 v7, v14, v7, s72
	v_add3_u32 v3, v15, v3, s72
	v_and_b32_e32 v11, 0xffff0000, v11
	v_and_b32_e32 v10, 0xffff0000, v10
	v_or_b32_sdwa v11, v11, v3 dst_sel:DWORD dst_unused:UNUSED_PAD src0_sel:DWORD src1_sel:WORD_1
	v_or_b32_sdwa v10, v10, v7 dst_sel:DWORD dst_unused:UNUSED_PAD src0_sel:DWORD src1_sel:WORD_1
	global_store_dwordx2 v[4:5], v[10:11], off offset:16
	s_nop 1
	v_mov_b64_e32 v[10:11], v[96:97]
	v_mov_b64_e32 v[12:13], v[98:99]
	v_mov_b32_e32 v32, v40
	v_mov_b32_e32 v33, v42
	v_mov_b32_e32 v42, v41
	v_pk_mul_f32 v[32:33], v[32:33], v[6:7] op_sel_hi:[1,0]
	v_mov_b32_e32 v14, v10
	v_mov_b32_e32 v15, v12
	v_mov_b32_e32 v12, v11
	v_pk_mul_f32 v[10:11], v[42:43], v[6:7] op_sel_hi:[1,0]
	v_pk_fma_f32 v[14:15], v[0:1], v[14:15], v[32:33] op_sel_hi:[0,1,1]
	v_mov_b32_e32 v33, v74
	v_pk_fma_f32 v[10:11], v[0:1], v[12:13], v[10:11] op_sel_hi:[0,1,1]
	v_mov_b32_e32 v74, v73
	v_mov_b32_e32 v32, v72
	v_pk_fma_f32 v[10:11], v[74:75], v[2:3], v[10:11] op_sel_hi:[1,0,1]
	v_pk_fma_f32 v[14:15], v[32:33], v[2:3], v[14:15] op_sel_hi:[1,0,1]
	v_and_b32_sdwa v12, v11, v225 dst_sel:DWORD dst_unused:UNUSED_PAD src0_sel:WORD_1 src1_sel:DWORD
	v_and_b32_sdwa v13, v10, v225 dst_sel:DWORD dst_unused:UNUSED_PAD src0_sel:WORD_1 src1_sel:DWORD
	v_and_b32_sdwa v3, v15, v225 dst_sel:DWORD dst_unused:UNUSED_PAD src0_sel:WORD_1 src1_sel:DWORD
	v_and_b32_sdwa v7, v14, v225 dst_sel:DWORD dst_unused:UNUSED_PAD src0_sel:WORD_1 src1_sel:DWORD
	v_add3_u32 v11, v11, v12, s72
	v_add3_u32 v10, v10, v13, s72
	v_add3_u32 v7, v14, v7, s72
	v_add3_u32 v3, v15, v3, s72
	v_and_b32_e32 v11, 0xffff0000, v11
	v_and_b32_e32 v10, 0xffff0000, v10
	v_or_b32_sdwa v11, v11, v3 dst_sel:DWORD dst_unused:UNUSED_PAD src0_sel:DWORD src1_sel:WORD_1
	v_or_b32_sdwa v10, v10, v7 dst_sel:DWORD dst_unused:UNUSED_PAD src0_sel:DWORD src1_sel:WORD_1
	global_store_dwordx2 v[4:5], v[10:11], off offset:32
	s_nop 1
	v_mov_b64_e32 v[10:11], v[100:101]
	v_mov_b64_e32 v[12:13], v[102:103]
	v_mov_b32_e32 v32, v44
	v_mov_b32_e32 v33, v46
	v_mov_b32_e32 v46, v45
	v_mov_b32_e32 v14, v10
	v_mov_b32_e32 v15, v12
	v_mov_b32_e32 v12, v11
	v_pk_mul_f32 v[14:15], v[0:1], v[14:15] op_sel_hi:[0,1]
	v_pk_mul_f32 v[10:11], v[0:1], v[12:13] op_sel_hi:[0,1]
	v_pk_fma_f32 v[14:15], v[32:33], v[6:7], v[14:15] op_sel_hi:[1,0,1]
	v_mov_b32_e32 v33, v78
	v_pk_fma_f32 v[10:11], v[46:47], v[6:7], v[10:11] op_sel_hi:[1,0,1]
	v_mov_b32_e32 v78, v77
	v_mov_b32_e32 v32, v76
	v_pk_fma_f32 v[10:11], v[78:79], v[2:3], v[10:11] op_sel_hi:[1,0,1]
	v_pk_fma_f32 v[14:15], v[32:33], v[2:3], v[14:15] op_sel_hi:[1,0,1]
	v_and_b32_sdwa v12, v11, v225 dst_sel:DWORD dst_unused:UNUSED_PAD src0_sel:WORD_1 src1_sel:DWORD
	v_and_b32_sdwa v13, v10, v225 dst_sel:DWORD dst_unused:UNUSED_PAD src0_sel:WORD_1 src1_sel:DWORD
	v_and_b32_sdwa v3, v15, v225 dst_sel:DWORD dst_unused:UNUSED_PAD src0_sel:WORD_1 src1_sel:DWORD
	v_and_b32_sdwa v7, v14, v225 dst_sel:DWORD dst_unused:UNUSED_PAD src0_sel:WORD_1 src1_sel:DWORD
; __device__ __forceinline__ unsigned pk2(float lo, float hi) { return f2bf(lo) | (f2bf(hi) << 16); }
; __device__ __forceinline__ void phase_nsa_mfma(const PT a, unsigned char* ldsb, int tid, int lane, int wave, int bid, int nblk) {
;     ...
;             for (int i4 = 0; i4 < 4; ++i4) { const int d = ds * 32 + i4 * 8 + 4 * hi; const size_t off = (size_t)tok * 1024 + hh * 64 + d;
;                 const f32x4 oc = *(const f32x4*)(ocmp + off);
;                 const float r0 = g0 * oc.x + g1 * Os[ds][i4 * 4 + 0] + g2 * Ow[ds][i4 * 4 + 0], r1 = g0 * oc.y + g1 * Os[ds][i4 * 4 + 1] + g2 * Ow[ds][i4 * 4 + 1];
;                 const float r2 = g0 * oc.z + g1 * Os[ds][i4 * 4 + 2] + g2 * Ow[ds][i4 * 4 + 2], r3 = g0 * oc.w + g1 * Os[ds][i4 * 4 + 3] + g2 * Ow[ds][i4 * 4 + 3];
;                 u32x2 w; w.x = pk2(r0, r1); w.y = pk2(r2, r3); *(u32x2*)(ob + (size_t)tok * KCAT + 512 + hh * 64 + d) = w; }
;     }
	v_add3_u32 v11, v11, v12, s72
	v_add3_u32 v10, v10, v13, s72
	v_add3_u32 v7, v14, v7, s72
	v_add3_u32 v3, v15, v3, s72
	v_and_b32_e32 v11, 0xffff0000, v11
	v_and_b32_e32 v10, 0xffff0000, v10
	v_or_b32_sdwa v11, v11, v3 dst_sel:DWORD dst_unused:UNUSED_PAD src0_sel:DWORD src1_sel:WORD_1
	v_or_b32_sdwa v10, v10, v7 dst_sel:DWORD dst_unused:UNUSED_PAD src0_sel:DWORD src1_sel:WORD_1
	global_store_dwordx2 v[4:5], v[10:11], off offset:48
	s_nop 1
	v_mov_b64_e32 v[10:11], v[106:107]
	v_mov_b64_e32 v[12:13], v[108:109]
	v_mov_b32_e32 v32, v16
	v_mov_b32_e32 v33, v18
	v_mov_b32_e32 v18, v17
	v_mov_b32_e32 v16, v20
	v_mov_b32_e32 v17, v22
	v_mov_b32_e32 v22, v21
	v_mov_b32_e32 v14, v10
	v_mov_b32_e32 v15, v12
	v_mov_b32_e32 v12, v11
	v_pk_mul_f32 v[14:15], v[0:1], v[14:15] op_sel_hi:[0,1]
	v_pk_mul_f32 v[10:11], v[0:1], v[12:13] op_sel_hi:[0,1]
	v_pk_fma_f32 v[14:15], v[32:33], v[6:7], v[14:15] op_sel_hi:[1,0,1]
	v_mov_b32_e32 v33, v50
	v_pk_fma_f32 v[10:11], v[18:19], v[6:7], v[10:11] op_sel_hi:[1,0,1]
	v_mov_b32_e32 v50, v49
	v_mov_b32_e32 v32, v48
	v_pk_fma_f32 v[10:11], v[50:51], v[2:3], v[10:11] op_sel_hi:[1,0,1]
	v_pk_fma_f32 v[14:15], v[32:33], v[2:3], v[14:15] op_sel_hi:[1,0,1]
	v_and_b32_sdwa v12, v11, v225 dst_sel:DWORD dst_unused:UNUSED_PAD src0_sel:WORD_1 src1_sel:DWORD
	v_and_b32_sdwa v13, v10, v225 dst_sel:DWORD dst_unused:UNUSED_PAD src0_sel:WORD_1 src1_sel:DWORD
	v_and_b32_sdwa v3, v15, v225 dst_sel:DWORD dst_unused:UNUSED_PAD src0_sel:WORD_1 src1_sel:DWORD
	v_and_b32_sdwa v7, v14, v225 dst_sel:DWORD dst_unused:UNUSED_PAD src0_sel:WORD_1 src1_sel:DWORD
	v_add3_u32 v11, v11, v12, s72
	v_add3_u32 v10, v10, v13, s72
	v_add3_u32 v7, v14, v7, s72
	v_add3_u32 v3, v15, v3, s72
	v_and_b32_e32 v11, 0xffff0000, v11
	v_and_b32_e32 v10, 0xffff0000, v10
	v_or_b32_sdwa v11, v11, v3 dst_sel:DWORD dst_unused:UNUSED_PAD src0_sel:DWORD src1_sel:WORD_1
	v_or_b32_sdwa v10, v10, v7 dst_sel:DWORD dst_unused:UNUSED_PAD src0_sel:DWORD src1_sel:WORD_1
	global_store_dwordx2 v[4:5], v[10:11], off offset:64
	s_nop 1
	v_mov_b64_e32 v[10:11], v[124:125]
	v_mov_b64_e32 v[12:13], v[126:127]
	v_mov_b32_e32 v14, v10
	v_mov_b32_e32 v15, v12
	v_mov_b32_e32 v12, v11
	v_pk_mul_f32 v[14:15], v[0:1], v[14:15] op_sel_hi:[0,1]
	v_pk_mul_f32 v[10:11], v[0:1], v[12:13] op_sel_hi:[0,1]
	v_pk_fma_f32 v[14:15], v[16:17], v[6:7], v[14:15] op_sel_hi:[1,0,1]
	v_mov_b32_e32 v17, v54
	v_pk_fma_f32 v[10:11], v[22:23], v[6:7], v[10:11] op_sel_hi:[1,0,1]
	v_mov_b32_e32 v54, v53
	v_mov_b32_e32 v16, v52
	v_pk_fma_f32 v[10:11], v[54:55], v[2:3], v[10:11] op_sel_hi:[1,0,1]
	v_pk_fma_f32 v[14:15], v[16:17], v[2:3], v[14:15] op_sel_hi:[1,0,1]
	v_and_b32_sdwa v12, v11, v225 dst_sel:DWORD dst_unused:UNUSED_PAD src0_sel:WORD_1 src1_sel:DWORD
	v_and_b32_sdwa v13, v10, v225 dst_sel:DWORD dst_unused:UNUSED_PAD src0_sel:WORD_1 src1_sel:DWORD
	v_and_b32_sdwa v3, v15, v225 dst_sel:DWORD dst_unused:UNUSED_PAD src0_sel:WORD_1 src1_sel:DWORD
	v_and_b32_sdwa v7, v14, v225 dst_sel:DWORD dst_unused:UNUSED_PAD src0_sel:WORD_1 src1_sel:DWORD
	v_add3_u32 v11, v11, v12, s72
	v_add3_u32 v10, v10, v13, s72
	v_add3_u32 v7, v14, v7, s72
	v_add3_u32 v3, v15, v3, s72
	v_and_b32_e32 v11, 0xffff0000, v11
	v_and_b32_e32 v10, 0xffff0000, v10
	v_or_b32_sdwa v11, v11, v3 dst_sel:DWORD dst_unused:UNUSED_PAD src0_sel:DWORD src1_sel:WORD_1
	v_or_b32_sdwa v10, v10, v7 dst_sel:DWORD dst_unused:UNUSED_PAD src0_sel:DWORD src1_sel:WORD_1
	global_store_dwordx2 v[4:5], v[10:11], off offset:80
	s_nop 1
	v_mov_b64_e32 v[10:11], v[128:129]
	v_mov_b64_e32 v[12:13], v[130:131]
	v_mov_b32_e32 v16, v24
	v_mov_b32_e32 v17, v26
	v_mov_b32_e32 v26, v25
	v_mov_b32_e32 v14, v10
	v_mov_b32_e32 v15, v12
	v_mov_b32_e32 v12, v11
	v_pk_mul_f32 v[14:15], v[0:1], v[14:15] op_sel_hi:[0,1]
	v_pk_mul_f32 v[10:11], v[0:1], v[12:13] op_sel_hi:[0,1]
	v_pk_fma_f32 v[14:15], v[16:17], v[6:7], v[14:15] op_sel_hi:[1,0,1]
	v_mov_b32_e32 v17, v58
	v_pk_fma_f32 v[10:11], v[26:27], v[6:7], v[10:11] op_sel_hi:[1,0,1]
	v_mov_b32_e32 v58, v57
	v_mov_b32_e32 v16, v56
	v_pk_fma_f32 v[10:11], v[58:59], v[2:3], v[10:11] op_sel_hi:[1,0,1]
	v_pk_fma_f32 v[14:15], v[16:17], v[2:3], v[14:15] op_sel_hi:[1,0,1]
	v_and_b32_sdwa v12, v11, v225 dst_sel:DWORD dst_unused:UNUSED_PAD src0_sel:WORD_1 src1_sel:DWORD
	v_and_b32_sdwa v13, v10, v225 dst_sel:DWORD dst_unused:UNUSED_PAD src0_sel:WORD_1 src1_sel:DWORD
	v_and_b32_sdwa v3, v15, v225 dst_sel:DWORD dst_unused:UNUSED_PAD src0_sel:WORD_1 src1_sel:DWORD
	v_and_b32_sdwa v7, v14, v225 dst_sel:DWORD dst_unused:UNUSED_PAD src0_sel:WORD_1 src1_sel:DWORD
	v_add3_u32 v11, v11, v12, s72
	v_add3_u32 v10, v10, v13, s72
	v_add3_u32 v7, v14, v7, s72
	v_add3_u32 v3, v15, v3, s72
	v_and_b32_e32 v11, 0xffff0000, v11
	v_and_b32_e32 v10, 0xffff0000, v10
	v_or_b32_sdwa v11, v11, v3 dst_sel:DWORD dst_unused:UNUSED_PAD src0_sel:DWORD src1_sel:WORD_1
	v_or_b32_sdwa v10, v10, v7 dst_sel:DWORD dst_unused:UNUSED_PAD src0_sel:DWORD src1_sel:WORD_1
	global_store_dwordx2 v[4:5], v[10:11], off offset:96
	s_nop 1
	v_mov_b64_e32 v[8:9], v[132:133]
	v_mov_b64_e32 v[10:11], v[134:135]
	v_mov_b32_e32 v14, v28
	v_mov_b32_e32 v15, v30
	v_mov_b32_e32 v30, v29
	v_mov_b32_e32 v12, v8
	v_mov_b32_e32 v13, v10
	v_mov_b32_e32 v10, v9
	v_pk_mul_f32 v[12:13], v[0:1], v[12:13] op_sel_hi:[0,1]
	v_pk_mul_f32 v[8:9], v[0:1], v[10:11] op_sel_hi:[0,1]
	v_pk_fma_f32 v[12:13], v[14:15], v[6:7], v[12:13] op_sel_hi:[1,0,1]
	v_mov_b32_e32 v14, v60
	v_mov_b32_e32 v15, v62
	v_pk_fma_f32 v[6:7], v[30:31], v[6:7], v[8:9] op_sel_hi:[1,0,1]
	v_mov_b32_e32 v62, v61
	v_pk_fma_f32 v[12:13], v[14:15], v[2:3], v[12:13] op_sel_hi:[1,0,1]
	v_pk_fma_f32 v[2:3], v[62:63], v[2:3], v[6:7] op_sel_hi:[1,0,1]
	v_and_b32_sdwa v0, v13, v225 dst_sel:DWORD dst_unused:UNUSED_PAD src0_sel:WORD_1 src1_sel:DWORD
	v_and_b32_sdwa v7, v3, v225 dst_sel:DWORD dst_unused:UNUSED_PAD src0_sel:WORD_1 src1_sel:DWORD
	v_and_b32_sdwa v8, v2, v225 dst_sel:DWORD dst_unused:UNUSED_PAD src0_sel:WORD_1 src1_sel:DWORD
	v_and_b32_sdwa v6, v12, v225 dst_sel:DWORD dst_unused:UNUSED_PAD src0_sel:WORD_1 src1_sel:DWORD
	v_add3_u32 v3, v3, v7, s72
	v_add3_u32 v2, v2, v8, s72
	v_add3_u32 v6, v12, v6, s72
	v_add3_u32 v0, v13, v0, s72
	v_and_b32_e32 v3, 0xffff0000, v3
	v_and_b32_e32 v2, 0xffff0000, v2
	v_or_b32_sdwa v3, v3, v0 dst_sel:DWORD dst_unused:UNUSED_PAD src0_sel:DWORD src1_sel:WORD_1
	v_or_b32_sdwa v2, v2, v6 dst_sel:DWORD dst_unused:UNUSED_PAD src0_sel:DWORD src1_sel:WORD_1
	global_store_dwordx2 v[4:5], v[2:3], off offset:112
	s_cbranch_scc0 .LBB0_216
